# FF2 residual epilogue head: four serialized gamma round trips + main group collapsed into one wait (gammas loaded into their final registers, scaled in place)
# speedup vs baseline: 1.0062x; 1.0062x over previous
.LBB0_1495:
	v_mbcnt_lo_u32_b32 v148, -1, 0
	v_mbcnt_hi_u32_b32 v148, -1, v148
	s_lshl_b32 s21, s29, 8
	v_ashrrev_i32_e32 v88, 1, v148
	v_and_b32_e32 v88, -8, v88
	s_or_b32 s21, s21, s51
	v_add_u32_e32 v144, s21, v88
	v_ashrrev_i32_e32 v145, 31, v144
	v_lshlrev_b64 v[206:207], 2, v[144:145]
	v_lshl_add_u64 v[92:93], s[14:15], 0, v[206:207]
	global_load_dwordx4 v[202:205], v[92:93], off
	global_load_dwordx4 v[198:201], v[92:93], off offset:16
	global_load_dwordx4 v[194:197], v[92:93], off offset:512
	global_load_dwordx4 v[190:193], v[92:93], off offset:528
	s_mov_b32 s30, 0x3fb504f3
	v_lshl_add_u64 v[146:147], s[16:17], 0, v[206:207]
	s_lshl_b32 s21, s28, 8
	s_add_i32 s21, s21, s50
	v_and_or_b32 v208, v148, 15, s21
	v_ashrrev_i32_e32 v209, 31, v208
	v_lshlrev_b64 v[148:149], 11, v[208:209]
	v_lshl_add_u64 v[148:149], s[10:11], 0, v[148:149]
	v_lshlrev_b64 v[210:211], 1, v[144:145]
	v_lshl_add_u64 v[144:145], v[148:149], 0, v[210:211]
	s_mov_b64 s[28:29], -1
	s_andn2_b64 vcc, exec, s[4:5]
	global_load_dwordx4 v[100:103], v[146:147], off
	global_load_dwordx4 v[96:99], v[146:147], off offset:16
	global_load_dwordx4 v[92:95], v[146:147], off offset:512
	global_load_dwordx4 v[88:91], v[146:147], off offset:528
	v_lshl_add_u64 v[146:147], v[208:209], 3, s[12:13]
	global_load_dwordx2 v[218:219], v[146:147], off
	v_lshlrev_b64 v[146:147], 12, v[208:209]
	v_lshl_add_u64 v[146:147], s[6:7], 0, v[146:147]
	v_lshl_add_u64 v[216:217], v[146:147], 0, v[206:207]
	global_load_dwordx4 v[222:225], v[216:217], off
	global_load_dwordx4 v[226:229], v[216:217], off offset:16
	global_load_dwordx4 v[234:237], v[144:145], off
	global_load_dwordx4 v[176:179], v[216:217], off offset:512
	global_load_dwordx4 v[172:175], v[216:217], off offset:528
	global_load_dwordx4 v[164:167], v[144:145], off offset:256
	v_or_b32_e32 v144, 16, v208
	v_ashrrev_i32_e32 v145, 31, v144
	v_lshl_add_u64 v[146:147], v[144:145], 3, s[12:13]
	global_load_dwordx2 v[214:215], v[146:147], off
	v_lshlrev_b64 v[146:147], 12, v[144:145]
	v_lshl_add_u64 v[146:147], s[6:7], 0, v[146:147]
	v_lshl_add_u64 v[212:213], v[146:147], 0, v[206:207]
	global_load_dwordx4 v[168:171], v[212:213], off
	global_load_dwordx4 v[160:163], v[212:213], off offset:16
	v_lshlrev_b64 v[144:145], 11, v[144:145]
	v_lshl_add_u64 v[144:145], s[10:11], 0, v[144:145]
	v_lshl_add_u64 v[144:145], v[144:145], 0, v[210:211]
	global_load_dwordx4 v[156:159], v[144:145], off
	global_load_dwordx4 v[152:155], v[212:213], off offset:512
	global_load_dwordx4 v[148:151], v[212:213], off offset:528
	s_nop 0
	global_load_dwordx4 v[144:147], v[144:145], off offset:256
	s_waitcnt vmcnt(0) lgkmcnt(0)
	v_pk_mul_f32 v[252:253], v[202:203], s[30:31] op_sel_hi:[1,0]
	v_pk_mul_f32 v[202:203], v[204:205], s[30:31] op_sel_hi:[1,0]
	v_mov_b64_e32 v[204:205], v[252:253]
	v_pk_mul_f32 v[252:253], v[198:199], s[30:31] op_sel_hi:[1,0]
	v_pk_mul_f32 v[198:199], v[200:201], s[30:31] op_sel_hi:[1,0]
	v_mov_b64_e32 v[200:201], v[252:253]
	v_pk_mul_f32 v[252:253], v[194:195], s[30:31] op_sel_hi:[1,0]
	v_pk_mul_f32 v[194:195], v[196:197], s[30:31] op_sel_hi:[1,0]
	v_mov_b64_e32 v[196:197], v[252:253]
	v_pk_mul_f32 v[252:253], v[190:191], s[30:31] op_sel_hi:[1,0]
	v_pk_mul_f32 v[190:191], v[192:193], s[30:31] op_sel_hi:[1,0]
	v_mov_b64_e32 v[192:193], v[252:253]
	v_sub_f32_e32 v225, v225, v218
	v_sub_f32_e32 v224, v224, v218
	v_sub_f32_e32 v223, v223, v218
	v_sub_f32_e32 v222, v222, v218
	v_pk_mul_f32 v[222:223], v[218:219], v[222:223] op_sel:[1,0]
	v_pk_mul_f32 v[224:225], v[218:219], v[224:225] op_sel:[1,0]
	v_pk_fma_f32 v[140:141], v[204:205], v[222:223], v[140:141]
	v_pk_fma_f32 v[142:143], v[202:203], v[224:225], v[142:143]
	v_sub_f32_e32 v223, v229, v218
	v_sub_f32_e32 v222, v228, v218
	v_sub_f32_e32 v225, v227, v218
	v_sub_f32_e32 v224, v226, v218
	v_pk_mul_f32 v[224:225], v[218:219], v[224:225] op_sel:[1,0]
	v_pk_mul_f32 v[222:223], v[218:219], v[222:223] op_sel:[1,0]
	v_pk_fma_f32 v[136:137], v[200:201], v[224:225], v[136:137]
	v_pk_fma_f32 v[138:139], v[198:199], v[222:223], v[138:139]
	v_pk_fma_f32 v[142:143], v[102:103], s[30:31], v[142:143] op_sel_hi:[1,0,1]
	v_pk_fma_f32 v[140:141], v[100:101], s[30:31], v[140:141] op_sel_hi:[1,0,1]
	v_pk_fma_f32 v[222:223], v[98:99], s[30:31], v[138:139] op_sel_hi:[1,0,1]
	v_pk_fma_f32 v[224:225], v[96:97], s[30:31], v[136:137] op_sel_hi:[1,0,1]
	v_lshlrev_b32_e32 v136, 16, v234
	v_and_b32_e32 v137, 0xffff0000, v234
	v_lshlrev_b32_e32 v138, 16, v235
	v_and_b32_e32 v139, 0xffff0000, v235
	v_pk_add_f32 v[136:137], v[140:141], v[136:137]
	v_pk_add_f32 v[138:139], v[142:143], v[138:139]
	v_lshlrev_b32_e32 v140, 16, v236
	v_and_b32_e32 v141, 0xffff0000, v236
	v_lshlrev_b32_e32 v142, 16, v237
	v_and_b32_e32 v143, 0xffff0000, v237
	v_pk_add_f32 v[140:141], v[224:225], v[140:141]
	v_pk_add_f32 v[142:143], v[222:223], v[142:143]
	global_store_dwordx4 v[216:217], v[136:139], off
	global_store_dwordx4 v[216:217], v[140:143], off offset:16
	s_nop 0
	v_sub_f32_e32 v137, v179, v218
	v_sub_f32_e32 v136, v178, v218
	v_sub_f32_e32 v139, v177, v218
	v_sub_f32_e32 v138, v176, v218
	v_pk_mul_f32 v[138:139], v[218:219], v[138:139] op_sel:[1,0]
	v_pk_mul_f32 v[136:137], v[218:219], v[136:137] op_sel:[1,0]
	v_pk_fma_f32 v[132:133], v[196:197], v[138:139], v[132:133]
	v_pk_fma_f32 v[134:135], v[194:195], v[136:137], v[134:135]
	v_sub_f32_e32 v137, v175, v218
	v_sub_f32_e32 v136, v174, v218
	v_sub_f32_e32 v139, v173, v218
	v_sub_f32_e32 v138, v172, v218
	v_pk_mul_f32 v[138:139], v[218:219], v[138:139] op_sel:[1,0]
	v_pk_mul_f32 v[136:137], v[218:219], v[136:137] op_sel:[1,0]
	v_pk_fma_f32 v[128:129], v[192:193], v[138:139], v[128:129]
	v_pk_fma_f32 v[130:131], v[190:191], v[136:137], v[130:131]
	v_pk_fma_f32 v[134:135], v[94:95], s[30:31], v[134:135] op_sel_hi:[1,0,1]
	v_pk_fma_f32 v[132:133], v[92:93], s[30:31], v[132:133] op_sel_hi:[1,0,1]
	v_pk_fma_f32 v[136:137], v[90:91], s[30:31], v[130:131] op_sel_hi:[1,0,1]
	v_pk_fma_f32 v[138:139], v[88:89], s[30:31], v[128:129] op_sel_hi:[1,0,1]
	v_lshlrev_b32_e32 v128, 16, v164
	v_and_b32_e32 v129, 0xffff0000, v164
	v_lshlrev_b32_e32 v130, 16, v165
	v_and_b32_e32 v131, 0xffff0000, v165
	v_pk_add_f32 v[128:129], v[132:133], v[128:129]
	v_pk_add_f32 v[130:131], v[134:135], v[130:131]
	v_lshlrev_b32_e32 v132, 16, v166
	v_and_b32_e32 v133, 0xffff0000, v166
	v_lshlrev_b32_e32 v134, 16, v167
	v_and_b32_e32 v135, 0xffff0000, v167
	v_pk_add_f32 v[132:133], v[138:139], v[132:133]
	v_pk_add_f32 v[134:135], v[136:137], v[134:135]
	global_store_dwordx4 v[216:217], v[128:131], off offset:512
	global_store_dwordx4 v[216:217], v[132:135], off offset:528
	s_nop 0
	v_sub_f32_e32 v129, v171, v214
	v_sub_f32_e32 v128, v170, v214
	v_sub_f32_e32 v131, v169, v214
	v_sub_f32_e32 v130, v168, v214
	v_pk_mul_f32 v[130:131], v[214:215], v[130:131] op_sel:[1,0]
	v_pk_mul_f32 v[128:129], v[214:215], v[128:129] op_sel:[1,0]
	v_pk_fma_f32 v[124:125], v[204:205], v[130:131], v[124:125]
	v_pk_fma_f32 v[126:127], v[202:203], v[128:129], v[126:127]
	v_sub_f32_e32 v129, v163, v214
	v_sub_f32_e32 v128, v162, v214
	v_sub_f32_e32 v131, v161, v214
	v_sub_f32_e32 v130, v160, v214
	v_pk_mul_f32 v[130:131], v[214:215], v[130:131] op_sel:[1,0]
	v_pk_mul_f32 v[128:129], v[214:215], v[128:129] op_sel:[1,0]
	v_pk_fma_f32 v[120:121], v[200:201], v[130:131], v[120:121]
	v_pk_fma_f32 v[122:123], v[198:199], v[128:129], v[122:123]
	v_pk_fma_f32 v[126:127], v[102:103], s[30:31], v[126:127] op_sel_hi:[1,0,1]
	v_pk_fma_f32 v[124:125], v[100:101], s[30:31], v[124:125] op_sel_hi:[1,0,1]
	v_pk_fma_f32 v[128:129], v[98:99], s[30:31], v[122:123] op_sel_hi:[1,0,1]
	v_pk_fma_f32 v[130:131], v[96:97], s[30:31], v[120:121] op_sel_hi:[1,0,1]
	v_lshlrev_b32_e32 v120, 16, v156
	v_and_b32_e32 v121, 0xffff0000, v156
	v_lshlrev_b32_e32 v122, 16, v157
	v_and_b32_e32 v123, 0xffff0000, v157
	v_pk_add_f32 v[120:121], v[124:125], v[120:121]
	v_pk_add_f32 v[122:123], v[126:127], v[122:123]
	v_lshlrev_b32_e32 v124, 16, v158
	v_and_b32_e32 v125, 0xffff0000, v158
	v_lshlrev_b32_e32 v126, 16, v159
	v_and_b32_e32 v127, 0xffff0000, v159
	v_pk_add_f32 v[124:125], v[130:131], v[124:125]
	v_pk_add_f32 v[126:127], v[128:129], v[126:127]
	global_store_dwordx4 v[212:213], v[120:123], off
	global_store_dwordx4 v[212:213], v[124:127], off offset:16
	s_nop 0
	v_sub_f32_e32 v121, v155, v214
	v_sub_f32_e32 v120, v154, v214
	v_sub_f32_e32 v123, v153, v214
	v_sub_f32_e32 v122, v152, v214
	v_pk_mul_f32 v[122:123], v[214:215], v[122:123] op_sel:[1,0]
	v_pk_mul_f32 v[120:121], v[214:215], v[120:121] op_sel:[1,0]
	v_pk_fma_f32 v[116:117], v[196:197], v[122:123], v[116:117]
	v_pk_fma_f32 v[118:119], v[194:195], v[120:121], v[118:119]
	v_sub_f32_e32 v121, v151, v214
	v_sub_f32_e32 v120, v150, v214
	v_sub_f32_e32 v123, v149, v214
	v_sub_f32_e32 v122, v148, v214
	v_pk_mul_f32 v[122:123], v[214:215], v[122:123] op_sel:[1,0]
	v_pk_mul_f32 v[120:121], v[214:215], v[120:121] op_sel:[1,0]
	v_pk_fma_f32 v[112:113], v[192:193], v[122:123], v[112:113]
	v_pk_fma_f32 v[114:115], v[190:191], v[120:121], v[114:115]
	v_pk_fma_f32 v[118:119], v[94:95], s[30:31], v[118:119] op_sel_hi:[1,0,1]
	v_pk_fma_f32 v[116:117], v[92:93], s[30:31], v[116:117] op_sel_hi:[1,0,1]
	v_pk_fma_f32 v[120:121], v[90:91], s[30:31], v[114:115] op_sel_hi:[1,0,1]
	v_pk_fma_f32 v[122:123], v[88:89], s[30:31], v[112:113] op_sel_hi:[1,0,1]
	v_lshlrev_b32_e32 v112, 16, v144
	v_and_b32_e32 v113, 0xffff0000, v144
	v_lshlrev_b32_e32 v114, 16, v145
	v_and_b32_e32 v115, 0xffff0000, v145
	v_pk_add_f32 v[112:113], v[116:117], v[112:113]
	v_pk_add_f32 v[114:115], v[118:119], v[114:115]
	v_lshlrev_b32_e32 v116, 16, v146
	v_and_b32_e32 v117, 0xffff0000, v146
	v_lshlrev_b32_e32 v118, 16, v147
	v_and_b32_e32 v119, 0xffff0000, v147
	v_pk_add_f32 v[116:117], v[122:123], v[116:117]
	v_pk_add_f32 v[118:119], v[120:121], v[118:119]
	global_store_dwordx4 v[212:213], v[112:115], off offset:512
	global_store_dwordx4 v[212:213], v[116:119], off offset:528
	s_nop 0
	v_or_b32_e32 v112, 32, v208
	v_ashrrev_i32_e32 v113, 31, v112
	v_lshl_add_u64 v[114:115], v[112:113], 3, s[12:13]
	global_load_dwordx2 v[162:163], v[114:115], off
	v_lshlrev_b64 v[114:115], 12, v[112:113]
	v_lshl_add_u64 v[114:115], s[6:7], 0, v[114:115]
	v_lshl_add_u64 v[164:165], v[114:115], 0, v[206:207]
	global_load_dwordx4 v[114:117], v[164:165], off
	global_load_dwordx4 v[118:121], v[164:165], off offset:16
	v_lshlrev_b64 v[112:113], 11, v[112:113]
	v_lshl_add_u64 v[112:113], s[10:11], 0, v[112:113]
	v_lshl_add_u64 v[112:113], v[112:113], 0, v[210:211]
	global_load_dwordx4 v[122:125], v[112:113], off
	global_load_dwordx4 v[126:129], v[164:165], off offset:512
	global_load_dwordx4 v[130:133], v[164:165], off offset:528
	global_load_dwordx4 v[134:137], v[112:113], off offset:256
	v_or_b32_e32 v112, 48, v208
	v_ashrrev_i32_e32 v113, 31, v112
	v_lshl_add_u64 v[138:139], v[112:113], 3, s[12:13]
	global_load_dwordx2 v[166:167], v[138:139], off
	v_lshlrev_b64 v[138:139], 12, v[112:113]
	v_lshl_add_u64 v[138:139], s[6:7], 0, v[138:139]
	v_lshlrev_b64 v[112:113], 11, v[112:113]
	v_lshl_add_u64 v[146:147], s[10:11], 0, v[112:113]
	v_lshl_add_u64 v[112:113], v[138:139], 0, v[206:207]
	global_load_dwordx4 v[138:141], v[112:113], off
	global_load_dwordx4 v[142:145], v[112:113], off offset:16
	v_lshl_add_u64 v[158:159], v[146:147], 0, v[210:211]
	global_load_dwordx4 v[146:149], v[158:159], off
	global_load_dwordx4 v[150:153], v[112:113], off offset:512
	global_load_dwordx4 v[154:157], v[112:113], off offset:528
	s_nop 0
	global_load_dwordx4 v[158:161], v[158:159], off offset:256
	s_waitcnt vmcnt(0) lgkmcnt(0)
	v_sub_f32_e32 v117, v117, v162
	v_sub_f32_e32 v116, v116, v162
	v_sub_f32_e32 v115, v115, v162
	v_sub_f32_e32 v114, v114, v162
	v_pk_mul_f32 v[114:115], v[162:163], v[114:115] op_sel:[1,0]
	v_pk_mul_f32 v[116:117], v[162:163], v[116:117] op_sel:[1,0]
	v_pk_fma_f32 v[108:109], v[204:205], v[114:115], v[108:109]
	v_pk_fma_f32 v[110:111], v[202:203], v[116:117], v[110:111]
	v_sub_f32_e32 v115, v121, v162
	v_sub_f32_e32 v114, v120, v162
	v_sub_f32_e32 v117, v119, v162
	v_sub_f32_e32 v116, v118, v162
	v_pk_mul_f32 v[116:117], v[162:163], v[116:117] op_sel:[1,0]
	v_pk_mul_f32 v[114:115], v[162:163], v[114:115] op_sel:[1,0]
	v_pk_fma_f32 v[104:105], v[200:201], v[116:117], v[104:105]
	v_pk_fma_f32 v[106:107], v[198:199], v[114:115], v[106:107]
	v_pk_fma_f32 v[110:111], v[102:103], s[30:31], v[110:111] op_sel_hi:[1,0,1]
	v_pk_fma_f32 v[108:109], v[100:101], s[30:31], v[108:109] op_sel_hi:[1,0,1]
	v_pk_fma_f32 v[114:115], v[98:99], s[30:31], v[106:107] op_sel_hi:[1,0,1]
	v_pk_fma_f32 v[116:117], v[96:97], s[30:31], v[104:105] op_sel_hi:[1,0,1]
	v_lshlrev_b32_e32 v104, 16, v122
	v_and_b32_e32 v105, 0xffff0000, v122
	v_lshlrev_b32_e32 v106, 16, v123
	v_and_b32_e32 v107, 0xffff0000, v123
	v_pk_add_f32 v[104:105], v[108:109], v[104:105]
	v_pk_add_f32 v[106:107], v[110:111], v[106:107]
	v_lshlrev_b32_e32 v108, 16, v124
	v_and_b32_e32 v109, 0xffff0000, v124
	v_lshlrev_b32_e32 v110, 16, v125
	v_and_b32_e32 v111, 0xffff0000, v125
	v_pk_add_f32 v[108:109], v[116:117], v[108:109]
	v_pk_add_f32 v[110:111], v[114:115], v[110:111]
	global_store_dwordx4 v[164:165], v[104:107], off
	global_store_dwordx4 v[164:165], v[108:111], off offset:16
	s_nop 0
	v_sub_f32_e32 v105, v129, v162
	v_sub_f32_e32 v104, v128, v162
	v_sub_f32_e32 v107, v127, v162
	v_sub_f32_e32 v106, v126, v162
	v_pk_mul_f32 v[106:107], v[162:163], v[106:107] op_sel:[1,0]
	v_pk_mul_f32 v[104:105], v[162:163], v[104:105] op_sel:[1,0]
	v_pk_fma_f32 v[84:85], v[196:197], v[106:107], v[84:85]
	v_pk_fma_f32 v[86:87], v[194:195], v[104:105], v[86:87]
	v_sub_f32_e32 v105, v133, v162
	v_sub_f32_e32 v104, v132, v162
	v_sub_f32_e32 v107, v131, v162
	v_sub_f32_e32 v106, v130, v162
	v_pk_mul_f32 v[106:107], v[162:163], v[106:107] op_sel:[1,0]
	v_pk_mul_f32 v[104:105], v[162:163], v[104:105] op_sel:[1,0]
	v_pk_fma_f32 v[80:81], v[192:193], v[106:107], v[80:81]
	v_pk_fma_f32 v[82:83], v[190:191], v[104:105], v[82:83]
	v_pk_fma_f32 v[86:87], v[94:95], s[30:31], v[86:87] op_sel_hi:[1,0,1]
	v_pk_fma_f32 v[84:85], v[92:93], s[30:31], v[84:85] op_sel_hi:[1,0,1]
	v_pk_fma_f32 v[104:105], v[90:91], s[30:31], v[82:83] op_sel_hi:[1,0,1]
	v_pk_fma_f32 v[106:107], v[88:89], s[30:31], v[80:81] op_sel_hi:[1,0,1]
	v_lshlrev_b32_e32 v80, 16, v134
	v_and_b32_e32 v81, 0xffff0000, v134
	v_lshlrev_b32_e32 v82, 16, v135
	v_and_b32_e32 v83, 0xffff0000, v135
	v_pk_add_f32 v[80:81], v[84:85], v[80:81]
	v_pk_add_f32 v[82:83], v[86:87], v[82:83]
	v_lshlrev_b32_e32 v84, 16, v136
	v_and_b32_e32 v85, 0xffff0000, v136
	v_lshlrev_b32_e32 v86, 16, v137
	v_and_b32_e32 v87, 0xffff0000, v137
	v_pk_add_f32 v[84:85], v[106:107], v[84:85]
	v_pk_add_f32 v[86:87], v[104:105], v[86:87]
	global_store_dwordx4 v[164:165], v[80:83], off offset:512
	global_store_dwordx4 v[164:165], v[84:87], off offset:528
	s_nop 0
	v_sub_f32_e32 v81, v141, v166
	v_sub_f32_e32 v80, v140, v166
	v_sub_f32_e32 v83, v139, v166
	v_sub_f32_e32 v82, v138, v166
	v_pk_mul_f32 v[82:83], v[166:167], v[82:83] op_sel:[1,0]
	v_pk_mul_f32 v[80:81], v[166:167], v[80:81] op_sel:[1,0]
	v_pk_fma_f32 v[76:77], v[204:205], v[82:83], v[76:77]
	v_pk_fma_f32 v[78:79], v[202:203], v[80:81], v[78:79]
	v_sub_f32_e32 v81, v145, v166
	v_sub_f32_e32 v80, v144, v166
	v_sub_f32_e32 v83, v143, v166
	v_sub_f32_e32 v82, v142, v166
	v_pk_mul_f32 v[82:83], v[166:167], v[82:83] op_sel:[1,0]
	v_pk_mul_f32 v[80:81], v[166:167], v[80:81] op_sel:[1,0]
	v_pk_fma_f32 v[72:73], v[200:201], v[82:83], v[72:73]
	v_pk_fma_f32 v[74:75], v[198:199], v[80:81], v[74:75]
	v_pk_fma_f32 v[78:79], v[102:103], s[30:31], v[78:79] op_sel_hi:[1,0,1]
	v_pk_fma_f32 v[76:77], v[100:101], s[30:31], v[76:77] op_sel_hi:[1,0,1]
	v_pk_fma_f32 v[80:81], v[98:99], s[30:31], v[74:75] op_sel_hi:[1,0,1]
	v_pk_fma_f32 v[82:83], v[96:97], s[30:31], v[72:73] op_sel_hi:[1,0,1]
	v_lshlrev_b32_e32 v72, 16, v146
	v_and_b32_e32 v73, 0xffff0000, v146
	v_lshlrev_b32_e32 v74, 16, v147
	v_and_b32_e32 v75, 0xffff0000, v147
	v_pk_add_f32 v[72:73], v[76:77], v[72:73]
	v_pk_add_f32 v[74:75], v[78:79], v[74:75]
	v_lshlrev_b32_e32 v76, 16, v148
	v_and_b32_e32 v77, 0xffff0000, v148
	v_lshlrev_b32_e32 v78, 16, v149
	v_and_b32_e32 v79, 0xffff0000, v149
	v_pk_add_f32 v[76:77], v[82:83], v[76:77]
	v_pk_add_f32 v[78:79], v[80:81], v[78:79]
	global_store_dwordx4 v[112:113], v[72:75], off
	global_store_dwordx4 v[112:113], v[76:79], off offset:16
	s_nop 0
	v_sub_f32_e32 v73, v153, v166
	v_sub_f32_e32 v72, v152, v166
	v_sub_f32_e32 v75, v151, v166
	v_sub_f32_e32 v74, v150, v166
	v_pk_mul_f32 v[74:75], v[166:167], v[74:75] op_sel:[1,0]
	v_pk_mul_f32 v[72:73], v[166:167], v[72:73] op_sel:[1,0]
	v_pk_fma_f32 v[68:69], v[196:197], v[74:75], v[68:69]
	v_pk_fma_f32 v[70:71], v[194:195], v[72:73], v[70:71]
	v_sub_f32_e32 v73, v157, v166
	v_sub_f32_e32 v72, v156, v166
	v_sub_f32_e32 v75, v155, v166
	v_sub_f32_e32 v74, v154, v166
	v_pk_mul_f32 v[74:75], v[166:167], v[74:75] op_sel:[1,0]
	v_pk_mul_f32 v[72:73], v[166:167], v[72:73] op_sel:[1,0]
	v_pk_fma_f32 v[64:65], v[192:193], v[74:75], v[64:65]
	v_pk_fma_f32 v[66:67], v[190:191], v[72:73], v[66:67]
	v_pk_fma_f32 v[70:71], v[94:95], s[30:31], v[70:71] op_sel_hi:[1,0,1]
	v_pk_fma_f32 v[68:69], v[92:93], s[30:31], v[68:69] op_sel_hi:[1,0,1]
	v_pk_fma_f32 v[72:73], v[90:91], s[30:31], v[66:67] op_sel_hi:[1,0,1]
	v_pk_fma_f32 v[74:75], v[88:89], s[30:31], v[64:65] op_sel_hi:[1,0,1]
	v_lshlrev_b32_e32 v64, 16, v158
	v_and_b32_e32 v65, 0xffff0000, v158
	v_lshlrev_b32_e32 v66, 16, v159
	v_and_b32_e32 v67, 0xffff0000, v159
	v_pk_add_f32 v[64:65], v[68:69], v[64:65]
	v_pk_add_f32 v[66:67], v[70:71], v[66:67]
	v_lshlrev_b32_e32 v68, 16, v160
	v_and_b32_e32 v69, 0xffff0000, v160
	v_lshlrev_b32_e32 v70, 16, v161
	v_and_b32_e32 v71, 0xffff0000, v161
	v_pk_add_f32 v[68:69], v[74:75], v[68:69]
	v_pk_add_f32 v[70:71], v[72:73], v[70:71]
	global_store_dwordx4 v[112:113], v[64:67], off offset:512
	global_store_dwordx4 v[112:113], v[68:71], off offset:528
	s_nop 0
	v_add_u32_e32 v64, 0x80, v208
	v_ashrrev_i32_e32 v65, 31, v64
	v_lshl_add_u64 v[66:67], v[64:65], 3, s[12:13]
	global_load_dwordx2 v[86:87], v[66:67], off
	v_lshlrev_b64 v[66:67], 12, v[64:65]
	v_lshl_add_u64 v[66:67], s[6:7], 0, v[66:67]
	v_lshl_add_u64 v[132:133], v[66:67], 0, v[206:207]
	global_load_dwordx4 v[66:69], v[132:133], off
	global_load_dwordx4 v[70:73], v[132:133], off offset:16
	v_lshlrev_b64 v[64:65], 11, v[64:65]
	v_lshl_add_u64 v[64:65], s[10:11], 0, v[64:65]
	v_lshl_add_u64 v[64:65], v[64:65], 0, v[210:211]
	global_load_dwordx4 v[74:77], v[64:65], off
	global_load_dwordx4 v[78:81], v[132:133], off offset:512
	global_load_dwordx4 v[82:85], v[132:133], off offset:528
	global_load_dwordx4 v[104:107], v[64:65], off offset:256
	v_add_u32_e32 v64, 0x90, v208
	v_ashrrev_i32_e32 v65, 31, v64
	v_lshl_add_u64 v[108:109], v[64:65], 3, s[12:13]
	global_load_dwordx2 v[134:135], v[108:109], off
	v_lshlrev_b64 v[108:109], 12, v[64:65]
	v_lshl_add_u64 v[108:109], s[6:7], 0, v[108:109]
	v_lshlrev_b64 v[64:65], 11, v[64:65]
	v_lshl_add_u64 v[116:117], s[10:11], 0, v[64:65]
	v_lshl_add_u64 v[64:65], v[108:109], 0, v[206:207]
	global_load_dwordx4 v[108:111], v[64:65], off
	global_load_dwordx4 v[112:115], v[64:65], off offset:16
	v_lshl_add_u64 v[128:129], v[116:117], 0, v[210:211]
	global_load_dwordx4 v[116:119], v[128:129], off
	global_load_dwordx4 v[120:123], v[64:65], off offset:512
	global_load_dwordx4 v[124:127], v[64:65], off offset:528
	s_nop 0
	global_load_dwordx4 v[128:131], v[128:129], off offset:256
	s_waitcnt vmcnt(0) lgkmcnt(0)
	v_sub_f32_e32 v69, v69, v86
	v_sub_f32_e32 v68, v68, v86
	v_sub_f32_e32 v67, v67, v86
	v_sub_f32_e32 v66, v66, v86
	v_pk_mul_f32 v[66:67], v[86:87], v[66:67] op_sel:[1,0]
	v_pk_mul_f32 v[68:69], v[86:87], v[68:69] op_sel:[1,0]
	v_pk_fma_f32 v[60:61], v[204:205], v[66:67], v[60:61]
	v_pk_fma_f32 v[62:63], v[202:203], v[68:69], v[62:63]
	v_sub_f32_e32 v67, v73, v86
	v_sub_f32_e32 v66, v72, v86
	v_sub_f32_e32 v69, v71, v86
	v_sub_f32_e32 v68, v70, v86
	v_pk_mul_f32 v[68:69], v[86:87], v[68:69] op_sel:[1,0]
	v_pk_mul_f32 v[66:67], v[86:87], v[66:67] op_sel:[1,0]
	v_pk_fma_f32 v[56:57], v[200:201], v[68:69], v[56:57]
	v_pk_fma_f32 v[58:59], v[198:199], v[66:67], v[58:59]
	v_pk_fma_f32 v[62:63], v[102:103], s[30:31], v[62:63] op_sel_hi:[1,0,1]
	v_pk_fma_f32 v[60:61], v[100:101], s[30:31], v[60:61] op_sel_hi:[1,0,1]
	v_pk_fma_f32 v[66:67], v[98:99], s[30:31], v[58:59] op_sel_hi:[1,0,1]
	v_pk_fma_f32 v[68:69], v[96:97], s[30:31], v[56:57] op_sel_hi:[1,0,1]
	v_lshlrev_b32_e32 v56, 16, v74
	v_and_b32_e32 v57, 0xffff0000, v74
	v_lshlrev_b32_e32 v58, 16, v75
	v_and_b32_e32 v59, 0xffff0000, v75
	v_pk_add_f32 v[56:57], v[60:61], v[56:57]
	v_pk_add_f32 v[58:59], v[62:63], v[58:59]
	v_lshlrev_b32_e32 v60, 16, v76
	v_and_b32_e32 v61, 0xffff0000, v76
	v_lshlrev_b32_e32 v62, 16, v77
	v_and_b32_e32 v63, 0xffff0000, v77
	v_pk_add_f32 v[60:61], v[68:69], v[60:61]
	v_pk_add_f32 v[62:63], v[66:67], v[62:63]
	global_store_dwordx4 v[132:133], v[56:59], off
	global_store_dwordx4 v[132:133], v[60:63], off offset:16
	s_nop 0
	v_sub_f32_e32 v57, v81, v86
	v_sub_f32_e32 v56, v80, v86
	v_sub_f32_e32 v59, v79, v86
	v_sub_f32_e32 v58, v78, v86
	v_pk_mul_f32 v[58:59], v[86:87], v[58:59] op_sel:[1,0]
	v_pk_mul_f32 v[56:57], v[86:87], v[56:57] op_sel:[1,0]
	v_pk_fma_f32 v[52:53], v[196:197], v[58:59], v[52:53]
	v_pk_fma_f32 v[54:55], v[194:195], v[56:57], v[54:55]
	v_sub_f32_e32 v57, v85, v86
	v_sub_f32_e32 v56, v84, v86
	v_sub_f32_e32 v59, v83, v86
	v_sub_f32_e32 v58, v82, v86
	v_pk_mul_f32 v[58:59], v[86:87], v[58:59] op_sel:[1,0]
	v_pk_mul_f32 v[56:57], v[86:87], v[56:57] op_sel:[1,0]
	v_pk_fma_f32 v[48:49], v[192:193], v[58:59], v[48:49]
	v_pk_fma_f32 v[50:51], v[190:191], v[56:57], v[50:51]
	v_pk_fma_f32 v[54:55], v[94:95], s[30:31], v[54:55] op_sel_hi:[1,0,1]
	v_pk_fma_f32 v[52:53], v[92:93], s[30:31], v[52:53] op_sel_hi:[1,0,1]
	v_pk_fma_f32 v[56:57], v[90:91], s[30:31], v[50:51] op_sel_hi:[1,0,1]
	v_pk_fma_f32 v[58:59], v[88:89], s[30:31], v[48:49] op_sel_hi:[1,0,1]
	v_lshlrev_b32_e32 v48, 16, v104
	v_and_b32_e32 v49, 0xffff0000, v104
	v_lshlrev_b32_e32 v50, 16, v105
	v_and_b32_e32 v51, 0xffff0000, v105
	v_pk_add_f32 v[48:49], v[52:53], v[48:49]
	v_pk_add_f32 v[50:51], v[54:55], v[50:51]
	v_lshlrev_b32_e32 v52, 16, v106
	v_and_b32_e32 v53, 0xffff0000, v106
	v_lshlrev_b32_e32 v54, 16, v107
	v_and_b32_e32 v55, 0xffff0000, v107
	v_pk_add_f32 v[52:53], v[58:59], v[52:53]
	v_pk_add_f32 v[54:55], v[56:57], v[54:55]
	global_store_dwordx4 v[132:133], v[48:51], off offset:512
	global_store_dwordx4 v[132:133], v[52:55], off offset:528
	s_nop 0
	v_sub_f32_e32 v49, v111, v134
	v_sub_f32_e32 v48, v110, v134
	v_sub_f32_e32 v51, v109, v134
	v_sub_f32_e32 v50, v108, v134
	v_pk_mul_f32 v[50:51], v[134:135], v[50:51] op_sel:[1,0]
	v_pk_mul_f32 v[48:49], v[134:135], v[48:49] op_sel:[1,0]
	v_pk_fma_f32 v[44:45], v[204:205], v[50:51], v[44:45]
	v_pk_fma_f32 v[46:47], v[202:203], v[48:49], v[46:47]
	v_sub_f32_e32 v49, v115, v134
	v_sub_f32_e32 v48, v114, v134
	v_sub_f32_e32 v51, v113, v134
	v_sub_f32_e32 v50, v112, v134
	v_pk_mul_f32 v[50:51], v[134:135], v[50:51] op_sel:[1,0]
	v_pk_mul_f32 v[48:49], v[134:135], v[48:49] op_sel:[1,0]
	v_pk_fma_f32 v[40:41], v[200:201], v[50:51], v[40:41]
	v_pk_fma_f32 v[42:43], v[198:199], v[48:49], v[42:43]
	v_pk_fma_f32 v[46:47], v[102:103], s[30:31], v[46:47] op_sel_hi:[1,0,1]
	v_pk_fma_f32 v[44:45], v[100:101], s[30:31], v[44:45] op_sel_hi:[1,0,1]
	v_pk_fma_f32 v[48:49], v[98:99], s[30:31], v[42:43] op_sel_hi:[1,0,1]
	v_pk_fma_f32 v[50:51], v[96:97], s[30:31], v[40:41] op_sel_hi:[1,0,1]
	v_lshlrev_b32_e32 v40, 16, v116
	v_and_b32_e32 v41, 0xffff0000, v116
	v_lshlrev_b32_e32 v42, 16, v117
	v_and_b32_e32 v43, 0xffff0000, v117
	v_pk_add_f32 v[40:41], v[44:45], v[40:41]
	v_pk_add_f32 v[42:43], v[46:47], v[42:43]
	v_lshlrev_b32_e32 v44, 16, v118
	v_and_b32_e32 v45, 0xffff0000, v118
	v_lshlrev_b32_e32 v46, 16, v119
	v_and_b32_e32 v47, 0xffff0000, v119
	v_pk_add_f32 v[44:45], v[50:51], v[44:45]
	v_pk_add_f32 v[46:47], v[48:49], v[46:47]
	global_store_dwordx4 v[64:65], v[40:43], off
	global_store_dwordx4 v[64:65], v[44:47], off offset:16
	s_nop 0
	v_sub_f32_e32 v41, v123, v134
	v_sub_f32_e32 v40, v122, v134
	v_sub_f32_e32 v43, v121, v134
	v_sub_f32_e32 v42, v120, v134
	v_pk_mul_f32 v[42:43], v[134:135], v[42:43] op_sel:[1,0]
	v_pk_mul_f32 v[40:41], v[134:135], v[40:41] op_sel:[1,0]
	v_pk_fma_f32 v[36:37], v[196:197], v[42:43], v[36:37]
	v_pk_fma_f32 v[38:39], v[194:195], v[40:41], v[38:39]
	v_sub_f32_e32 v41, v127, v134
	v_sub_f32_e32 v40, v126, v134
	v_sub_f32_e32 v43, v125, v134
	v_sub_f32_e32 v42, v124, v134
	v_pk_mul_f32 v[42:43], v[134:135], v[42:43] op_sel:[1,0]
	v_pk_mul_f32 v[40:41], v[134:135], v[40:41] op_sel:[1,0]
	v_pk_fma_f32 v[32:33], v[192:193], v[42:43], v[32:33]
	v_pk_fma_f32 v[34:35], v[190:191], v[40:41], v[34:35]
	v_pk_fma_f32 v[38:39], v[94:95], s[30:31], v[38:39] op_sel_hi:[1,0,1]
	v_pk_fma_f32 v[36:37], v[92:93], s[30:31], v[36:37] op_sel_hi:[1,0,1]
	v_pk_fma_f32 v[40:41], v[90:91], s[30:31], v[34:35] op_sel_hi:[1,0,1]
	v_pk_fma_f32 v[42:43], v[88:89], s[30:31], v[32:33] op_sel_hi:[1,0,1]
	v_lshlrev_b32_e32 v32, 16, v128
	v_and_b32_e32 v33, 0xffff0000, v128
	v_lshlrev_b32_e32 v34, 16, v129
	v_and_b32_e32 v35, 0xffff0000, v129
	v_pk_add_f32 v[32:33], v[36:37], v[32:33]
	v_pk_add_f32 v[34:35], v[38:39], v[34:35]
	v_lshlrev_b32_e32 v36, 16, v130
	v_and_b32_e32 v37, 0xffff0000, v130
	v_lshlrev_b32_e32 v38, 16, v131
	v_and_b32_e32 v39, 0xffff0000, v131
	v_pk_add_f32 v[36:37], v[42:43], v[36:37]
	v_pk_add_f32 v[38:39], v[40:41], v[38:39]
	global_store_dwordx4 v[64:65], v[32:35], off offset:512
	global_store_dwordx4 v[64:65], v[36:39], off offset:528
	s_nop 0
	v_add_u32_e32 v32, 0xa0, v208
	v_ashrrev_i32_e32 v33, 31, v32
	v_lshl_add_u64 v[34:35], v[32:33], 3, s[12:13]
	global_load_dwordx2 v[82:83], v[34:35], off
	v_lshlrev_b64 v[34:35], 12, v[32:33]
	v_lshl_add_u64 v[34:35], s[6:7], 0, v[34:35]
	v_lshl_add_u64 v[84:85], v[34:35], 0, v[206:207]
	global_load_dwordx4 v[34:37], v[84:85], off
	global_load_dwordx4 v[38:41], v[84:85], off offset:16
	v_lshlrev_b64 v[32:33], 11, v[32:33]
	v_lshl_add_u64 v[32:33], s[10:11], 0, v[32:33]
	v_lshl_add_u64 v[32:33], v[32:33], 0, v[210:211]
	global_load_dwordx4 v[42:45], v[32:33], off
	global_load_dwordx4 v[46:49], v[84:85], off offset:512
	global_load_dwordx4 v[50:53], v[84:85], off offset:528
	global_load_dwordx4 v[54:57], v[32:33], off offset:256
	v_add_u32_e32 v32, 0xb0, v208
	v_ashrrev_i32_e32 v33, 31, v32
	v_lshl_add_u64 v[58:59], v[32:33], 3, s[12:13]
	global_load_dwordx2 v[86:87], v[58:59], off
	v_lshlrev_b64 v[58:59], 12, v[32:33]
	v_lshl_add_u64 v[58:59], s[6:7], 0, v[58:59]
	v_lshlrev_b64 v[32:33], 11, v[32:33]
	v_lshl_add_u64 v[66:67], s[10:11], 0, v[32:33]
	v_lshl_add_u64 v[32:33], v[58:59], 0, v[206:207]
	global_load_dwordx4 v[58:61], v[32:33], off
	global_load_dwordx4 v[62:65], v[32:33], off offset:16
	v_lshl_add_u64 v[78:79], v[66:67], 0, v[210:211]
	global_load_dwordx4 v[66:69], v[78:79], off
	global_load_dwordx4 v[70:73], v[32:33], off offset:512
	global_load_dwordx4 v[74:77], v[32:33], off offset:528
	s_nop 0
	global_load_dwordx4 v[78:81], v[78:79], off offset:256
	s_waitcnt vmcnt(0) lgkmcnt(0)
	v_sub_f32_e32 v37, v37, v82
	v_sub_f32_e32 v36, v36, v82
	v_sub_f32_e32 v35, v35, v82
	v_sub_f32_e32 v34, v34, v82
	v_pk_mul_f32 v[34:35], v[82:83], v[34:35] op_sel:[1,0]
	v_pk_mul_f32 v[36:37], v[82:83], v[36:37] op_sel:[1,0]
	v_pk_fma_f32 v[28:29], v[204:205], v[34:35], v[28:29]
	v_pk_fma_f32 v[30:31], v[202:203], v[36:37], v[30:31]
	v_sub_f32_e32 v35, v41, v82
	v_sub_f32_e32 v34, v40, v82
	v_sub_f32_e32 v37, v39, v82
	v_sub_f32_e32 v36, v38, v82
	v_pk_mul_f32 v[36:37], v[82:83], v[36:37] op_sel:[1,0]
	v_pk_mul_f32 v[34:35], v[82:83], v[34:35] op_sel:[1,0]
	v_pk_fma_f32 v[24:25], v[200:201], v[36:37], v[24:25]
	v_pk_fma_f32 v[26:27], v[198:199], v[34:35], v[26:27]
	v_pk_fma_f32 v[30:31], v[102:103], s[30:31], v[30:31] op_sel_hi:[1,0,1]
	v_pk_fma_f32 v[28:29], v[100:101], s[30:31], v[28:29] op_sel_hi:[1,0,1]
	v_pk_fma_f32 v[34:35], v[98:99], s[30:31], v[26:27] op_sel_hi:[1,0,1]
	v_pk_fma_f32 v[36:37], v[96:97], s[30:31], v[24:25] op_sel_hi:[1,0,1]
	v_lshlrev_b32_e32 v24, 16, v42
	v_and_b32_e32 v25, 0xffff0000, v42
	v_lshlrev_b32_e32 v26, 16, v43
	v_and_b32_e32 v27, 0xffff0000, v43
	v_pk_add_f32 v[24:25], v[28:29], v[24:25]
	v_pk_add_f32 v[26:27], v[30:31], v[26:27]
	v_lshlrev_b32_e32 v28, 16, v44
	v_and_b32_e32 v29, 0xffff0000, v44
	v_lshlrev_b32_e32 v30, 16, v45
	v_and_b32_e32 v31, 0xffff0000, v45
	v_pk_add_f32 v[28:29], v[36:37], v[28:29]
	v_pk_add_f32 v[30:31], v[34:35], v[30:31]
	global_store_dwordx4 v[84:85], v[24:27], off
	global_store_dwordx4 v[84:85], v[28:31], off offset:16
	s_nop 0
	v_sub_f32_e32 v25, v49, v82
	v_sub_f32_e32 v24, v48, v82
	v_sub_f32_e32 v27, v47, v82
	v_sub_f32_e32 v26, v46, v82
	v_pk_mul_f32 v[26:27], v[82:83], v[26:27] op_sel:[1,0]
	v_pk_mul_f32 v[24:25], v[82:83], v[24:25] op_sel:[1,0]
	v_pk_fma_f32 v[20:21], v[196:197], v[26:27], v[20:21]
	v_pk_fma_f32 v[22:23], v[194:195], v[24:25], v[22:23]
	v_sub_f32_e32 v25, v53, v82
	v_sub_f32_e32 v24, v52, v82
	v_sub_f32_e32 v27, v51, v82
	v_sub_f32_e32 v26, v50, v82
	v_pk_mul_f32 v[26:27], v[82:83], v[26:27] op_sel:[1,0]
	v_pk_mul_f32 v[24:25], v[82:83], v[24:25] op_sel:[1,0]
	v_pk_fma_f32 v[16:17], v[192:193], v[26:27], v[16:17]
	v_pk_fma_f32 v[18:19], v[190:191], v[24:25], v[18:19]
	v_pk_fma_f32 v[22:23], v[94:95], s[30:31], v[22:23] op_sel_hi:[1,0,1]
	v_pk_fma_f32 v[20:21], v[92:93], s[30:31], v[20:21] op_sel_hi:[1,0,1]
	v_pk_fma_f32 v[24:25], v[90:91], s[30:31], v[18:19] op_sel_hi:[1,0,1]
	v_pk_fma_f32 v[26:27], v[88:89], s[30:31], v[16:17] op_sel_hi:[1,0,1]
	v_lshlrev_b32_e32 v16, 16, v54
	v_and_b32_e32 v17, 0xffff0000, v54
	v_lshlrev_b32_e32 v18, 16, v55
	v_and_b32_e32 v19, 0xffff0000, v55
	v_pk_add_f32 v[16:17], v[20:21], v[16:17]
	v_pk_add_f32 v[18:19], v[22:23], v[18:19]
	v_lshlrev_b32_e32 v20, 16, v56
	v_and_b32_e32 v21, 0xffff0000, v56
	v_lshlrev_b32_e32 v22, 16, v57
	v_and_b32_e32 v23, 0xffff0000, v57
	v_pk_add_f32 v[20:21], v[26:27], v[20:21]
	v_pk_add_f32 v[22:23], v[24:25], v[22:23]
	global_store_dwordx4 v[84:85], v[16:19], off offset:512
	global_store_dwordx4 v[84:85], v[20:23], off offset:528
	s_nop 0
	v_sub_f32_e32 v17, v61, v86
	v_sub_f32_e32 v16, v60, v86
	v_sub_f32_e32 v19, v59, v86
	v_sub_f32_e32 v18, v58, v86
	v_pk_mul_f32 v[18:19], v[86:87], v[18:19] op_sel:[1,0]
	v_pk_mul_f32 v[16:17], v[86:87], v[16:17] op_sel:[1,0]
	v_pk_fma_f32 v[12:13], v[204:205], v[18:19], v[12:13]
	v_pk_fma_f32 v[14:15], v[202:203], v[16:17], v[14:15]
	v_sub_f32_e32 v17, v65, v86
	v_sub_f32_e32 v16, v64, v86
	v_sub_f32_e32 v19, v63, v86
	v_sub_f32_e32 v18, v62, v86
	v_pk_mul_f32 v[18:19], v[86:87], v[18:19] op_sel:[1,0]
	v_pk_mul_f32 v[16:17], v[86:87], v[16:17] op_sel:[1,0]
	v_pk_fma_f32 v[8:9], v[200:201], v[18:19], v[8:9]
	v_pk_fma_f32 v[10:11], v[198:199], v[16:17], v[10:11]
	v_pk_fma_f32 v[14:15], v[102:103], s[30:31], v[14:15] op_sel_hi:[1,0,1]
	v_pk_fma_f32 v[12:13], v[100:101], s[30:31], v[12:13] op_sel_hi:[1,0,1]
	v_pk_fma_f32 v[16:17], v[98:99], s[30:31], v[10:11] op_sel_hi:[1,0,1]
	v_pk_fma_f32 v[18:19], v[96:97], s[30:31], v[8:9] op_sel_hi:[1,0,1]
	v_lshlrev_b32_e32 v8, 16, v66
	v_and_b32_e32 v9, 0xffff0000, v66
	v_lshlrev_b32_e32 v10, 16, v67
	v_and_b32_e32 v11, 0xffff0000, v67
	v_pk_add_f32 v[8:9], v[12:13], v[8:9]
	v_pk_add_f32 v[10:11], v[14:15], v[10:11]
	v_lshlrev_b32_e32 v12, 16, v68
	v_and_b32_e32 v13, 0xffff0000, v68
	v_lshlrev_b32_e32 v14, 16, v69
	v_and_b32_e32 v15, 0xffff0000, v69
	v_pk_add_f32 v[12:13], v[18:19], v[12:13]
	v_pk_add_f32 v[14:15], v[16:17], v[14:15]
	global_store_dwordx4 v[32:33], v[8:11], off
	global_store_dwordx4 v[32:33], v[12:15], off offset:16
	s_nop 0
	v_sub_f32_e32 v9, v73, v86
	v_sub_f32_e32 v8, v72, v86
	v_sub_f32_e32 v11, v71, v86
	v_sub_f32_e32 v10, v70, v86
	v_pk_mul_f32 v[10:11], v[86:87], v[10:11] op_sel:[1,0]
	v_pk_mul_f32 v[8:9], v[86:87], v[8:9] op_sel:[1,0]
	v_pk_fma_f32 v[4:5], v[196:197], v[10:11], v[4:5]
	v_pk_fma_f32 v[6:7], v[194:195], v[8:9], v[6:7]
	v_sub_f32_e32 v9, v77, v86
	v_sub_f32_e32 v8, v76, v86
	v_sub_f32_e32 v11, v75, v86
	v_sub_f32_e32 v10, v74, v86
	v_pk_mul_f32 v[10:11], v[86:87], v[10:11] op_sel:[1,0]
	v_pk_mul_f32 v[8:9], v[86:87], v[8:9] op_sel:[1,0]
	v_pk_fma_f32 v[0:1], v[192:193], v[10:11], v[0:1]
	v_pk_fma_f32 v[2:3], v[190:191], v[8:9], v[2:3]
	v_pk_fma_f32 v[6:7], v[94:95], s[30:31], v[6:7] op_sel_hi:[1,0,1]
	v_pk_fma_f32 v[4:5], v[92:93], s[30:31], v[4:5] op_sel_hi:[1,0,1]
	v_pk_fma_f32 v[8:9], v[90:91], s[30:31], v[2:3] op_sel_hi:[1,0,1]
	v_pk_fma_f32 v[10:11], v[88:89], s[30:31], v[0:1] op_sel_hi:[1,0,1]
	v_lshlrev_b32_e32 v0, 16, v78
	v_and_b32_e32 v1, 0xffff0000, v78
	v_lshlrev_b32_e32 v2, 16, v79
	v_and_b32_e32 v3, 0xffff0000, v79
	v_pk_add_f32 v[0:1], v[4:5], v[0:1]
	v_pk_add_f32 v[2:3], v[6:7], v[2:3]
	v_lshlrev_b32_e32 v4, 16, v80
	v_and_b32_e32 v5, 0xffff0000, v80
	v_lshlrev_b32_e32 v6, 16, v81
	v_and_b32_e32 v7, 0xffff0000, v81
	v_pk_add_f32 v[4:5], v[10:11], v[4:5]
	v_pk_add_f32 v[6:7], v[8:9], v[6:7]
	global_store_dwordx4 v[32:33], v[0:3], off offset:512
	global_store_dwordx4 v[32:33], v[4:7], off offset:528
	s_cbranch_vccnz .LBB0_1484
	s_andn2_b64 vcc, exec, s[8:9]
	s_cbranch_vccnz .LBB0_1483
	s_barrier
	s_branch .LBB0_1483
